# LayerNorm-phase output stores issued write-through (sc1) so the release write-back at the following grid barrier has less dirty L2 to flush
# baseline (speedup 1.0000x reference)
.LBB0_89:
	v_cmp_lt_i32_e32 vcc, s70, v28
	v_mov_b64_e32 v[4:5], v[28:29]
	v_mov_b64_e32 v[2:3], v[30:31]
	s_and_saveexec_b64 s[26:27], vcc
	v_add_u32_e32 v0, 0xffff8000, v28
	v_lshlrev_b64 v[2:3], 12, v[0:1]
	v_mov_b32_e32 v0, v28
	v_lshl_add_u64 v[2:3], s[40:41], 0, v[2:3]
	v_mov_b64_e32 v[4:5], v[0:1]
	s_or_b64 exec, exec, s[26:27]
	v_cmp_lt_i32_e32 vcc, s70, v28
	v_mov_b32_e32 v0, s11
	v_mov_b32_e32 v6, s43
	s_and_b64 vcc, s[2:3], vcc
	v_cndmask_b32_e32 v7, v0, v6, vcc
	v_mov_b32_e32 v0, s10
	v_mov_b32_e32 v6, s42
	v_cndmask_b32_e32 v6, v0, v6, vcc
	v_lshlrev_b64 v[38:39], 11, v[4:5]
	v_min_i32_e32 v0, 0x8000, v28
	v_lshl_add_u64 v[4:5], v[6:7], 0, v[38:39]
	v_lshlrev_b32_e32 v6, 1, v18
	v_mov_b32_e32 v7, v1
	v_ashrrev_i32_e32 v0, 13, v0
	s_mul_i32 s26, s44, 5
	v_lshl_add_u64 v[4:5], v[4:5], 0, v[6:7]
	v_add_u32_e32 v33, s26, v0
	global_load_dwordx2 v[16:17], v[4:5], off
	global_load_dwordx2 v[66:67], v[4:5], off offset:512
	global_load_dwordx2 v[68:69], v[4:5], off offset:1024
	global_load_dwordx2 v[70:71], v[4:5], off offset:1536
	v_mad_i64_i32 v[46:47], s[26:27], v33, s4, v[24:25]
	global_load_dwordx4 v[4:7], v[46:47], off
	global_load_dwordx4 v[8:11], v[46:47], off offset:1024
	global_load_dwordx4 v[12:15], v[46:47], off offset:2048
	v_lshlrev_b32_e32 v0, 2, v18
	global_load_dwordx4 v[46:49], v[46:47], off offset:3072
	v_lshl_add_u64 v[72:73], v[2:3], 0, v[0:1]
	global_load_dwordx4 v[50:53], v[72:73], off
	global_load_dwordx4 v[54:57], v[72:73], off offset:1024
	global_load_dwordx4 v[58:61], v[72:73], off offset:2048
	global_load_dwordx4 v[62:65], v[72:73], off offset:3072
	s_mov_b32 s26, 0x3fb504f3
	s_waitcnt vmcnt(11)
	v_lshlrev_b32_e32 v2, 16, v16
	v_and_b32_e32 v3, 0xffff0000, v16
	s_waitcnt vmcnt(10)
	v_lshlrev_b32_e32 v74, 16, v66
	v_and_b32_e32 v75, 0xffff0000, v66
	v_lshlrev_b32_e32 v66, 16, v67
	v_and_b32_e32 v67, 0xffff0000, v67
	s_waitcnt vmcnt(9)
	v_lshlrev_b32_e32 v76, 16, v68
	v_and_b32_e32 v77, 0xffff0000, v68
	v_lshlrev_b32_e32 v68, 16, v69
	v_and_b32_e32 v69, 0xffff0000, v69
	s_waitcnt vmcnt(8)
	v_lshlrev_b32_e32 v78, 16, v70
	v_and_b32_e32 v79, 0xffff0000, v70
	v_lshlrev_b32_e32 v70, 16, v71
	v_and_b32_e32 v71, 0xffff0000, v71
	s_waitcnt vmcnt(7)
	v_pk_mul_f32 v[2:3], v[4:5], v[2:3]
	v_lshlrev_b32_e32 v16, 16, v17
	v_and_b32_e32 v17, 0xffff0000, v17
	s_waitcnt vmcnt(6)
	v_pk_mul_f32 v[4:5], v[10:11], v[66:67]
	s_waitcnt vmcnt(5)
	v_pk_mul_f32 v[10:11], v[14:15], v[68:69]
	s_waitcnt vmcnt(4)
	v_pk_mul_f32 v[14:15], v[48:49], v[70:71]
	s_waitcnt vmcnt(3)
	v_pk_fma_f32 v[48:49], v[50:51], s[26:27], v[2:3] op_sel_hi:[1,0,1]
	v_pk_mul_f32 v[6:7], v[6:7], v[16:17]
	v_add_f32_e32 v2, 0, v48
	v_pk_mul_f32 v[16:17], v[46:47], v[78:79]
	v_pk_fma_f32 v[46:47], v[52:53], s[26:27], v[6:7] op_sel_hi:[1,0,1]
	v_add_f32_e32 v2, v49, v2
	v_pk_mul_f32 v[8:9], v[8:9], v[74:75]
	v_add_f32_e32 v2, v46, v2
	s_waitcnt vmcnt(2)
	v_pk_fma_f32 v[52:53], v[54:55], s[26:27], v[8:9] op_sel_hi:[1,0,1]
	v_add_f32_e32 v2, v47, v2
	v_add_f32_e32 v2, v52, v2
	v_pk_fma_f32 v[50:51], v[56:57], s[26:27], v[4:5] op_sel_hi:[1,0,1]
	v_add_f32_e32 v2, v53, v2
	v_pk_mul_f32 v[12:13], v[12:13], v[76:77]
	v_add_f32_e32 v2, v50, v2
	s_waitcnt vmcnt(1)
	v_pk_fma_f32 v[12:13], v[58:59], s[26:27], v[12:13] op_sel_hi:[1,0,1]
	v_add_f32_e32 v2, v51, v2
	v_add_f32_e32 v2, v12, v2
	v_pk_fma_f32 v[10:11], v[60:61], s[26:27], v[10:11] op_sel_hi:[1,0,1]
	v_add_f32_e32 v2, v13, v2
	v_add_f32_e32 v2, v10, v2
	s_waitcnt vmcnt(0)
	v_pk_fma_f32 v[16:17], v[62:63], s[26:27], v[16:17] op_sel_hi:[1,0,1]
	v_add_f32_e32 v2, v11, v2
	v_add_f32_e32 v2, v16, v2
	v_pk_fma_f32 v[14:15], v[64:65], s[26:27], v[14:15] op_sel_hi:[1,0,1]
	v_add_f32_e32 v2, v17, v2
	v_add_f32_e32 v2, v14, v2
	v_add_f32_e32 v2, v15, v2
	v_mov_b32_e32 v3, v2
	s_nop 1
	v_permlane32_swap_b32_e32 v3, v2
	s_waitcnt lgkmcnt(0)
	v_add_f32_e32 v2, v2, v3
	v_mov_b32_e32 v3, v2
	s_nop 1
	v_permlane16_swap_b32_e32 v3, v2
	s_waitcnt lgkmcnt(0)
	v_add_f32_e32 v2, v2, v3
	s_nop 1
	v_mov_b32_dpp v3, v2 row_ror:8 row_mask:0xf bank_mask:0xf
	s_waitcnt lgkmcnt(0)
	v_add_f32_e32 v2, v2, v3
	s_nop 1
	v_mov_b32_dpp v3, v2 quad_perm:[3,2,1,0] row_mask:0xf bank_mask:0xf
	s_nop 1
	v_mov_b32_dpp v3, v3 row_half_mirror row_mask:0xf bank_mask:0xf
	s_waitcnt lgkmcnt(0)
	v_add_f32_e32 v2, v2, v3
	s_nop 1
	v_mov_b32_dpp v3, v2 quad_perm:[2,3,0,1] row_mask:0xf bank_mask:0xf
	s_waitcnt lgkmcnt(0)
	v_add_f32_e32 v35, v2, v3
	s_nop 1
	v_mov_b32_dpp v37, v35 quad_perm:[1,0,3,2] row_mask:0xf bank_mask:0xf
	s_waitcnt lgkmcnt(0)
	v_add_f32_e32 v35, v35, v37
	v_mul_f32_e32 v54, 0x3a800000, v35
	v_pk_add_f32 v[48:49], v[48:49], v[54:55] op_sel_hi:[1,0] neg_lo:[0,1] neg_hi:[0,1]
	v_pk_add_f32 v[46:47], v[46:47], v[54:55] op_sel_hi:[1,0] neg_lo:[0,1] neg_hi:[0,1]
	v_pk_add_f32 v[58:59], v[10:11], v[54:55] op_sel_hi:[1,0] neg_lo:[0,1] neg_hi:[0,1]
	v_pk_mul_f32 v[10:11], v[48:49], v[48:49]
	v_pk_add_f32 v[56:57], v[12:13], v[54:55] op_sel_hi:[1,0] neg_lo:[0,1] neg_hi:[0,1]
	v_pk_mul_f32 v[12:13], v[46:47], v[46:47]
	v_add_f32_e32 v10, v10, v11
	v_pk_add_f32 v[52:53], v[52:53], v[54:55] op_sel_hi:[1,0] neg_lo:[0,1] neg_hi:[0,1]
	v_add_f32_e32 v10, v12, v10
	v_pk_add_f32 v[50:51], v[50:51], v[54:55] op_sel_hi:[1,0] neg_lo:[0,1] neg_hi:[0,1]
	v_pk_add_f32 v[60:61], v[16:17], v[54:55] op_sel_hi:[1,0] neg_lo:[0,1] neg_hi:[0,1]
	v_pk_add_f32 v[54:55], v[14:15], v[54:55] op_sel_hi:[1,0] neg_lo:[0,1] neg_hi:[0,1]
	v_pk_mul_f32 v[14:15], v[52:53], v[52:53]
	v_add_f32_e32 v10, v13, v10
	v_add_f32_e32 v10, v14, v10
	v_pk_mul_f32 v[16:17], v[50:51], v[50:51]
	v_add_f32_e32 v10, v15, v10
	v_add_f32_e32 v10, v16, v10
	v_pk_mul_f32 v[62:63], v[56:57], v[56:57]
	v_add_f32_e32 v10, v17, v10
	v_add_f32_e32 v10, v62, v10
	v_pk_mul_f32 v[64:65], v[58:59], v[58:59]
	v_add_f32_e32 v10, v63, v10
	v_add_f32_e32 v10, v64, v10
	v_pk_mul_f32 v[66:67], v[60:61], v[60:61]
	v_add_f32_e32 v10, v65, v10
	v_add_f32_e32 v10, v66, v10
	v_pk_mul_f32 v[68:69], v[54:55], v[54:55]
	v_add_f32_e32 v10, v67, v10
	v_add_f32_e32 v10, v68, v10
	v_add_f32_e32 v10, v69, v10
	v_mov_b32_e32 v11, v10
	s_nop 1
	v_permlane32_swap_b32_e32 v11, v10
	s_waitcnt lgkmcnt(0)
	v_add_f32_e32 v10, v10, v11
	v_mov_b32_e32 v11, v10
	s_nop 1
	v_permlane16_swap_b32_e32 v11, v10
	s_waitcnt lgkmcnt(0)
	v_add_f32_e32 v10, v10, v11
	s_nop 1
	v_mov_b32_dpp v11, v10 row_ror:8 row_mask:0xf bank_mask:0xf
	s_waitcnt lgkmcnt(0)
	v_add_f32_e32 v10, v10, v11
	s_nop 1
	v_mov_b32_dpp v11, v10 quad_perm:[3,2,1,0] row_mask:0xf bank_mask:0xf
	s_nop 1
	v_mov_b32_dpp v11, v11 row_half_mirror row_mask:0xf bank_mask:0xf
	s_waitcnt lgkmcnt(0)
	v_add_f32_e32 v10, v10, v11
	s_nop 1
	v_mov_b32_dpp v11, v10 quad_perm:[2,3,0,1] row_mask:0xf bank_mask:0xf
	s_waitcnt lgkmcnt(0)
	v_add_f32_e32 v10, v10, v11
	s_nop 1
	v_mov_b32_dpp v11, v10 quad_perm:[1,0,3,2] row_mask:0xf bank_mask:0xf
	s_waitcnt lgkmcnt(0)
	v_add_f32_e32 v10, v10, v11
	v_fmamk_f32 v10, v10, 0x3a800000, v208
	v_mul_f32_e32 v11, 0x4b800000, v10
	v_cmp_gt_f32_e32 vcc, s5, v10
	s_nop 1
	v_cndmask_b32_e32 v10, v10, v11, vcc
	v_rsq_f32_e32 v10, v10
	s_nop 0
	v_mul_f32_e32 v11, 0x45800000, v10
	v_cndmask_b32_e32 v62, v10, v11, vcc
	v_pk_mul_f32 v[10:11], v[48:49], v[62:63] op_sel_hi:[1,0]
	v_pk_mul_f32 v[12:13], v[46:47], v[62:63] op_sel_hi:[1,0]
	v_pk_fma_f32 v[2:3], v[80:81], v[10:11], v[96:97]
	v_pk_fma_f32 v[4:5], v[82:83], v[12:13], v[98:99]
	global_store_dwordx4 v[72:73], v[2:5], off sc1
	v_pk_mul_f32 v[14:15], v[52:53], v[62:63] op_sel_hi:[1,0]
	v_pk_mul_f32 v[16:17], v[50:51], v[62:63] op_sel_hi:[1,0]
	v_pk_mul_f32 v[46:47], v[56:57], v[62:63] op_sel_hi:[1,0]
	v_pk_mul_f32 v[48:49], v[58:59], v[62:63] op_sel_hi:[1,0]
	v_pk_mul_f32 v[50:51], v[60:61], v[62:63] op_sel_hi:[1,0]
	v_pk_mul_f32 v[52:53], v[54:55], v[62:63] op_sel_hi:[1,0]
	s_andn2_b64 vcc, exec, s[12:13]
	v_pk_fma_f32 v[6:7], v[84:85], v[14:15], v[100:101]
	v_pk_fma_f32 v[8:9], v[86:87], v[16:17], v[102:103]
	global_store_dwordx4 v[72:73], v[6:9], off offset:1024 sc1
	v_pk_fma_f32 v[10:11], v[88:89], v[46:47], v[104:105]
	v_pk_fma_f32 v[12:13], v[90:91], v[48:49], v[106:107]
	global_store_dwordx4 v[72:73], v[10:13], off offset:2048 sc1
	v_pk_fma_f32 v[14:15], v[92:93], v[50:51], v[108:109]
	v_pk_fma_f32 v[16:17], v[94:95], v[52:53], v[110:111]
	global_store_dwordx4 v[72:73], v[14:17], off offset:3072 sc1
	s_cbranch_vccnz .LBB0_88
	v_add_f32_e32 v35, 0, v2
	v_add_f32_e32 v35, v3, v35
	v_add_f32_e32 v35, v4, v35
	v_add_f32_e32 v35, v5, v35
	v_add_f32_e32 v35, v6, v35
	v_add_f32_e32 v35, v7, v35
	v_add_f32_e32 v35, v8, v35
	v_add_f32_e32 v35, v9, v35
	v_add_f32_e32 v35, v10, v35
	v_add_f32_e32 v35, v11, v35
	v_add_f32_e32 v35, v12, v35
	v_add_f32_e32 v35, v13, v35
	v_add_f32_e32 v35, v14, v35
	v_add_f32_e32 v35, v15, v35
	v_add_f32_e32 v35, v16, v35
	v_add_f32_e32 v35, v17, v35
	v_mov_b32_e32 v37, v35
	s_nop 1
	v_permlane32_swap_b32_e32 v37, v35
	v_add_u32_e32 v33, 5, v33
	v_mov_b64_e32 v[46:47], s[18:19]
	v_mad_i64_i32 v[50:51], s[26:27], v33, s4, v[46:47]
	s_waitcnt lgkmcnt(0)
	v_add_f32_e32 v35, v35, v37
	v_mov_b32_e32 v37, v35
	s_nop 1
	v_permlane16_swap_b32_e32 v37, v35
	s_mov_b64 s[26:27], 0x1000
	v_lshl_add_u64 v[54:55], v[50:51], 0, s[26:27]
	v_lshl_add_u64 v[46:47], v[54:55], 0, v[0:1]
	global_load_dwordx4 v[112:115], v[46:47], off
	global_load_dwordx4 v[116:119], v[46:47], off offset:1024
	global_load_dwordx4 v[120:123], v[46:47], off offset:2048
	global_load_dwordx4 v[124:127], v[46:47], off offset:3072
	s_waitcnt lgkmcnt(0)
	v_add_f32_e32 v35, v35, v37
	s_nop 1
	v_mov_b32_dpp v37, v35 row_ror:8 row_mask:0xf bank_mask:0xf
	v_lshl_add_u64 v[56:57], v[50:51], 0, v[0:1]
	global_load_dwordx4 v[128:131], v[56:57], off
	global_load_dwordx4 v[132:135], v[56:57], off offset:1024
	global_load_dwordx4 v[136:139], v[56:57], off offset:2048
	global_load_dwordx4 v[140:143], v[56:57], off offset:3072
	v_lshl_add_u64 v[38:39], v[26:27], 0, v[38:39]
	s_waitcnt lgkmcnt(0)
	v_add_f32_e32 v35, v35, v37
	s_nop 1
	v_mov_b32_dpp v37, v35 quad_perm:[3,2,1,0] row_mask:0xf bank_mask:0xf
	s_nop 1
	v_mov_b32_dpp v37, v37 row_half_mirror row_mask:0xf bank_mask:0xf
	s_waitcnt lgkmcnt(0)
	v_add_f32_e32 v35, v35, v37
	s_nop 1
	v_mov_b32_dpp v37, v35 quad_perm:[2,3,0,1] row_mask:0xf bank_mask:0xf
	s_waitcnt lgkmcnt(0)
	v_add_f32_e32 v33, v35, v37
	s_nop 1
	v_mov_b32_dpp v35, v33 quad_perm:[1,0,3,2] row_mask:0xf bank_mask:0xf
	v_mov_b32_e32 v37, v1
	s_waitcnt lgkmcnt(0)
	v_add_f32_e32 v0, v33, v35
	v_mul_f32_e32 v0, 0x3a800000, v0
	v_pk_add_f32 v[2:3], v[2:3], v[0:1] op_sel_hi:[1,0] neg_lo:[0,1] neg_hi:[0,1]
	v_pk_add_f32 v[4:5], v[4:5], v[0:1] op_sel_hi:[1,0] neg_lo:[0,1] neg_hi:[0,1]
	v_pk_add_f32 v[58:59], v[8:9], v[0:1] op_sel_hi:[1,0] neg_lo:[0,1] neg_hi:[0,1]
	v_pk_mul_f32 v[8:9], v[2:3], v[2:3]
	v_pk_add_f32 v[60:61], v[6:7], v[0:1] op_sel_hi:[1,0] neg_lo:[0,1] neg_hi:[0,1]
	v_pk_add_f32 v[12:13], v[12:13], v[0:1] op_sel_hi:[1,0] neg_lo:[0,1] neg_hi:[0,1]
	v_pk_add_f32 v[10:11], v[10:11], v[0:1] op_sel_hi:[1,0] neg_lo:[0,1] neg_hi:[0,1]
	v_pk_add_f32 v[16:17], v[16:17], v[0:1] op_sel_hi:[1,0] neg_lo:[0,1] neg_hi:[0,1]
	v_pk_add_f32 v[14:15], v[14:15], v[0:1] op_sel_hi:[1,0] neg_lo:[0,1] neg_hi:[0,1]
	v_pk_mul_f32 v[6:7], v[4:5], v[4:5]
	v_add_f32_e32 v0, v8, v9
	v_add_f32_e32 v0, v6, v0
	v_pk_mul_f32 v[64:65], v[60:61], v[60:61]
	v_add_f32_e32 v0, v7, v0
	v_add_f32_e32 v0, v64, v0
	v_pk_mul_f32 v[62:63], v[58:59], v[58:59]
	v_add_f32_e32 v0, v65, v0
	v_add_f32_e32 v0, v62, v0
	v_pk_mul_f32 v[68:69], v[10:11], v[10:11]
	v_add_f32_e32 v0, v63, v0
	v_add_f32_e32 v0, v68, v0
	v_pk_mul_f32 v[66:67], v[12:13], v[12:13]
	v_add_f32_e32 v0, v69, v0
	v_add_f32_e32 v0, v66, v0
	v_pk_mul_f32 v[72:73], v[14:15], v[14:15]
	v_add_f32_e32 v0, v67, v0
	v_add_f32_e32 v0, v72, v0
	v_pk_mul_f32 v[70:71], v[16:17], v[16:17]
	v_add_f32_e32 v0, v73, v0
	v_add_f32_e32 v0, v70, v0
	v_add_f32_e32 v0, v71, v0
	v_mov_b32_e32 v6, v0
	s_nop 1
	v_permlane32_swap_b32_e32 v6, v0
	v_mov_b32_e32 v33, v1
	v_mov_b32_e32 v35, v1
	s_waitcnt lgkmcnt(0)
	v_add_f32_e32 v0, v0, v6
	v_mov_b32_e32 v6, v0
	s_nop 1
	v_permlane16_swap_b32_e32 v6, v0
	s_waitcnt lgkmcnt(0)
	v_add_f32_e32 v0, v0, v6
	s_nop 1
	v_mov_b32_dpp v6, v0 row_ror:8 row_mask:0xf bank_mask:0xf
	s_waitcnt lgkmcnt(0)
	v_add_f32_e32 v0, v0, v6
	s_nop 1
	v_mov_b32_dpp v6, v0 quad_perm:[3,2,1,0] row_mask:0xf bank_mask:0xf
	s_nop 1
	v_mov_b32_dpp v6, v6 row_half_mirror row_mask:0xf bank_mask:0xf
	s_waitcnt vmcnt(0)
	v_pk_add_f32 v[8:9], v[114:115], 1.0 op_sel_hi:[1,0]
	s_waitcnt lgkmcnt(0)
	v_add_f32_e32 v0, v0, v6
	s_nop 1
	v_mov_b32_dpp v6, v0 quad_perm:[2,3,0,1] row_mask:0xf bank_mask:0xf
	v_pk_add_f32 v[46:47], v[112:113], 1.0 op_sel_hi:[1,0]
	s_waitcnt lgkmcnt(0)
	v_add_f32_e32 v0, v0, v6
	s_nop 1
	v_mov_b32_dpp v6, v0 quad_perm:[1,0,3,2] row_mask:0xf bank_mask:0xf
	s_waitcnt lgkmcnt(0)
	v_add_f32_e32 v0, v0, v6
	v_fmamk_f32 v0, v0, 0x3a800000, v208
	v_mul_f32_e32 v6, 0x4b800000, v0
	v_cmp_gt_f32_e32 vcc, s5, v0
	s_nop 1
	v_cndmask_b32_e32 v0, v0, v6, vcc
	v_rsq_f32_e32 v0, v0
	v_lshl_add_u64 v[6:7], v[54:55], 0, v[32:33]
	v_mul_f32_e32 v33, 0x45800000, v0
	v_cndmask_b32_e32 v0, v0, v33, vcc
	v_pk_mul_f32 v[2:3], v[2:3], v[0:1] op_sel_hi:[1,0]
	v_pk_mul_f32 v[4:5], v[4:5], v[0:1] op_sel_hi:[1,0]
	v_pk_fma_f32 v[2:3], v[46:47], v[2:3], v[128:129]
	v_pk_fma_f32 v[4:5], v[8:9], v[4:5], v[130:131]
	v_cvt_pk_bf16_f32 v2, v2, v3
	v_cvt_pk_bf16_f32 v3, v4, v5
	global_store_dwordx2 v[38:39], v[2:3], off sc1
	v_pk_mul_f32 v[48:49], v[60:61], v[0:1] op_sel_hi:[1,0]
	v_pk_mul_f32 v[50:51], v[58:59], v[0:1] op_sel_hi:[1,0]
	v_lshl_add_u64 v[46:47], v[54:55], 0, v[34:35]
	v_pk_mul_f32 v[10:11], v[10:11], v[0:1] op_sel_hi:[1,0]
	v_pk_mul_f32 v[12:13], v[12:13], v[0:1] op_sel_hi:[1,0]
	v_pk_add_f32 v[2:3], v[116:117], 1.0 op_sel_hi:[1,0]
	v_pk_add_f32 v[4:5], v[118:119], 1.0 op_sel_hi:[1,0]
	v_pk_fma_f32 v[2:3], v[2:3], v[48:49], v[132:133]
	v_pk_fma_f32 v[4:5], v[4:5], v[50:51], v[134:135]
	v_cvt_pk_bf16_f32 v2, v2, v3
	v_cvt_pk_bf16_f32 v3, v4, v5
	global_store_dwordx2 v[38:39], v[2:3], off offset:512 sc1
	v_lshl_add_u64 v[46:47], v[54:55], 0, v[36:37]
	v_pk_add_f32 v[2:3], v[120:121], 1.0 op_sel_hi:[1,0]
	v_pk_add_f32 v[4:5], v[122:123], 1.0 op_sel_hi:[1,0]
	v_pk_fma_f32 v[2:3], v[2:3], v[10:11], v[136:137]
	v_pk_fma_f32 v[4:5], v[4:5], v[12:13], v[138:139]
	v_cvt_pk_bf16_f32 v2, v2, v3
	v_cvt_pk_bf16_f32 v3, v4, v5
	global_store_dwordx2 v[38:39], v[2:3], off offset:1024 sc1
	v_pk_mul_f32 v[10:11], v[14:15], v[0:1] op_sel_hi:[1,0]
	v_pk_mul_f32 v[12:13], v[16:17], v[0:1] op_sel_hi:[1,0]
	v_pk_add_f32 v[2:3], v[124:125], 1.0 op_sel_hi:[1,0]
	v_pk_add_f32 v[4:5], v[126:127], 1.0 op_sel_hi:[1,0]
	v_pk_fma_f32 v[2:3], v[2:3], v[10:11], v[140:141]
	v_pk_fma_f32 v[4:5], v[4:5], v[12:13], v[142:143]
	v_cvt_pk_bf16_f32 v2, v2, v3
	v_cvt_pk_bf16_f32 v3, v4, v5
	global_store_dwordx2 v[38:39], v[2:3], off offset:1536 sc1
	s_branch .LBB0_88

.LBB0_683:
	s_or_b64 exec, exec, s[14:15]
	v_lshl_add_u64 v[16:17], v[16:17], 0, v[0:1]
	global_load_dwordx4 v[24:27], v[16:17], off
	global_load_dwordx4 v[28:31], v[16:17], off offset:1024
	global_load_dwordx4 v[32:35], v[16:17], off offset:2048
	global_load_dwordx4 v[36:39], v[16:17], off offset:3072
	s_load_dwordx2 s[14:15], s[54:55], 0x130
	v_min_i32_e32 v13, 0x8000, v4
	v_ashrrev_i32_e32 v13, 13, v13
	v_mul_hi_i32_i24_e32 v17, 0x6000, v13
	v_mul_i32_i24_e32 v16, 0x6000, v13
	s_waitcnt lgkmcnt(0)
	v_lshl_add_u64 v[16:17], s[14:15], 0, v[16:17]
	s_mov_b64 s[14:15], 0x1000
	v_lshl_add_u64 v[48:49], v[16:17], 0, s[14:15]
	v_lshl_add_u64 v[40:41], v[48:49], 0, v[0:1]
	global_load_dwordx4 v[40:43], v[40:41], off
	v_lshl_add_u64 v[50:51], v[16:17], 0, v[0:1]
	global_load_dwordx4 v[44:47], v[50:51], off
	v_mov_b32_e32 v97, v1
	v_mov_b32_e32 v96, v8
	v_lshl_add_u64 v[90:91], v[48:49], 0, v[96:97]
	global_load_dwordx4 v[66:69], v[90:91], off
	v_mov_b32_e32 v96, v10
	v_lshl_add_u64 v[92:93], v[48:49], 0, v[96:97]
	global_load_dwordx4 v[70:73], v[92:93], off
	v_mov_b32_e32 v96, v12
	v_lshl_add_u64 v[94:95], v[48:49], 0, v[96:97]
	global_load_dwordx4 v[74:77], v[94:95], off
	global_load_dwordx4 v[78:81], v[50:51], off offset:1024
	global_load_dwordx4 v[82:85], v[50:51], off offset:2048
	global_load_dwordx4 v[86:89], v[50:51], off offset:3072
	v_lshlrev_b64 v[14:15], 11, v[14:15]
	v_lshl_add_u64 v[4:5], v[4:5], 0, s[8:9]
	s_mov_b32 s1, 0x83ff
	v_lshl_add_u64 v[6:7], v[6:7], 0, s[10:11]
	s_waitcnt vmcnt(11)
	v_add_f32_e32 v9, 0, v24
	v_add_f32_e32 v9, v25, v9
	v_add_f32_e32 v9, v26, v9
	v_add_f32_e32 v9, v27, v9
	s_waitcnt vmcnt(10)
	v_add_f32_e32 v9, v28, v9
	v_add_f32_e32 v9, v29, v9
	v_add_f32_e32 v9, v30, v9
	v_add_f32_e32 v9, v31, v9
	s_waitcnt vmcnt(9)
	v_add_f32_e32 v9, v32, v9
	v_add_f32_e32 v9, v33, v9
	v_add_f32_e32 v9, v34, v9
	v_add_f32_e32 v9, v35, v9
	s_waitcnt vmcnt(8)
	v_add_f32_e32 v9, v36, v9
	v_add_f32_e32 v9, v37, v9
	v_add_f32_e32 v9, v38, v9
	v_add_f32_e32 v9, v39, v9
	v_mov_b32_e32 v11, v9
	s_nop 1
	v_permlane32_swap_b32_e32 v11, v9
	s_waitcnt lgkmcnt(0)
	v_add_f32_e32 v9, v9, v11
	v_mov_b32_e32 v11, v9
	s_nop 1
	v_permlane16_swap_b32_e32 v11, v9
	s_waitcnt lgkmcnt(0)
	v_add_f32_e32 v9, v9, v11
	s_nop 1
	v_mov_b32_dpp v11, v9 row_ror:8 row_mask:0xf bank_mask:0xf
	s_waitcnt lgkmcnt(0)
	v_add_f32_e32 v9, v9, v11
	s_nop 1
	v_mov_b32_dpp v11, v9 quad_perm:[3,2,1,0] row_mask:0xf bank_mask:0xf
	s_nop 1
	v_mov_b32_dpp v11, v11 row_half_mirror row_mask:0xf bank_mask:0xf
	s_waitcnt lgkmcnt(0)
	v_add_f32_e32 v9, v9, v11
	s_nop 1
	v_mov_b32_dpp v11, v9 quad_perm:[2,3,0,1] row_mask:0xf bank_mask:0xf
	s_waitcnt lgkmcnt(0)
	v_add_f32_e32 v9, v9, v11
	s_nop 1
	v_mov_b32_dpp v11, v9 quad_perm:[1,0,3,2] row_mask:0xf bank_mask:0xf
	s_waitcnt lgkmcnt(0)
	v_add_f32_e32 v9, v9, v11
	v_mul_f32_e32 v16, 0x3a800000, v9
	v_pk_add_f32 v[24:25], v[24:25], v[16:17] op_sel_hi:[1,0] neg_lo:[0,1] neg_hi:[0,1]
	v_pk_add_f32 v[26:27], v[26:27], v[16:17] op_sel_hi:[1,0] neg_lo:[0,1] neg_hi:[0,1]
	v_pk_mul_f32 v[52:53], v[24:25], v[24:25]
	v_pk_add_f32 v[30:31], v[30:31], v[16:17] op_sel_hi:[1,0] neg_lo:[0,1] neg_hi:[0,1]
	v_pk_add_f32 v[28:29], v[28:29], v[16:17] op_sel_hi:[1,0] neg_lo:[0,1] neg_hi:[0,1]
	v_pk_add_f32 v[34:35], v[34:35], v[16:17] op_sel_hi:[1,0] neg_lo:[0,1] neg_hi:[0,1]
	v_pk_add_f32 v[32:33], v[32:33], v[16:17] op_sel_hi:[1,0] neg_lo:[0,1] neg_hi:[0,1]
	v_pk_add_f32 v[38:39], v[38:39], v[16:17] op_sel_hi:[1,0] neg_lo:[0,1] neg_hi:[0,1]
	v_pk_add_f32 v[36:37], v[36:37], v[16:17] op_sel_hi:[1,0] neg_lo:[0,1] neg_hi:[0,1]
	v_pk_mul_f32 v[16:17], v[26:27], v[26:27]
	v_add_f32_e32 v9, v52, v53
	v_add_f32_e32 v9, v16, v9
	v_pk_mul_f32 v[56:57], v[28:29], v[28:29]
	v_add_f32_e32 v9, v17, v9
	v_add_f32_e32 v9, v56, v9
	v_pk_mul_f32 v[54:55], v[30:31], v[30:31]
	v_add_f32_e32 v9, v57, v9
	v_add_f32_e32 v9, v54, v9
	v_pk_mul_f32 v[60:61], v[32:33], v[32:33]
	v_add_f32_e32 v9, v55, v9
	v_add_f32_e32 v9, v60, v9
	v_pk_mul_f32 v[58:59], v[34:35], v[34:35]
	v_add_f32_e32 v9, v61, v9
	v_add_f32_e32 v9, v58, v9
	v_pk_mul_f32 v[64:65], v[36:37], v[36:37]
	v_add_f32_e32 v9, v59, v9
	v_add_f32_e32 v9, v64, v9
	v_pk_mul_f32 v[62:63], v[38:39], v[38:39]
	v_add_f32_e32 v9, v65, v9
	v_add_f32_e32 v9, v62, v9
	v_add_f32_e32 v9, v63, v9
	v_mov_b32_e32 v11, v9
	s_nop 1
	v_permlane32_swap_b32_e32 v11, v9
	v_lshl_add_u64 v[52:53], v[2:3], 0, v[14:15]
	s_waitcnt lgkmcnt(0)
	v_add_f32_e32 v9, v9, v11
	v_mov_b32_e32 v11, v9
	s_nop 1
	v_permlane16_swap_b32_e32 v11, v9
	s_waitcnt lgkmcnt(0)
	v_add_f32_e32 v9, v9, v11
	s_nop 1
	v_mov_b32_dpp v11, v9 row_ror:8 row_mask:0xf bank_mask:0xf
	s_waitcnt lgkmcnt(0)
	v_add_f32_e32 v9, v9, v11
	s_nop 1
	v_mov_b32_dpp v11, v9 quad_perm:[3,2,1,0] row_mask:0xf bank_mask:0xf
	s_nop 1
	v_mov_b32_dpp v11, v11 row_half_mirror row_mask:0xf bank_mask:0xf
	s_waitcnt lgkmcnt(0)
	v_add_f32_e32 v9, v9, v11
	s_nop 1
	v_mov_b32_dpp v11, v9 quad_perm:[2,3,0,1] row_mask:0xf bank_mask:0xf
	s_waitcnt lgkmcnt(0)
	v_add_f32_e32 v11, v9, v11
	s_nop 1
	v_mov_b32_dpp v13, v11 quad_perm:[1,0,3,2] row_mask:0xf bank_mask:0xf
	v_mov_b32_e32 v9, v1
	s_waitcnt lgkmcnt(0)
	v_add_f32_e32 v11, v11, v13
	v_fmamk_f32 v11, v11, 0x3a800000, v208
	v_mul_f32_e32 v13, 0x4b800000, v11
	v_cmp_gt_f32_e32 vcc, s5, v11
	s_nop 1
	v_cndmask_b32_e32 v11, v11, v13, vcc
	v_rsq_f32_e32 v11, v11
	v_mov_b32_e32 v13, v1
	v_mul_f32_e32 v9, 0x45800000, v11
	v_cndmask_b32_e32 v98, v11, v9, vcc
	v_cmp_lt_i32_e32 vcc, s1, v4
	s_or_b64 s[12:13], vcc, s[12:13]
	s_waitcnt vmcnt(0)
	v_pk_mul_f32 v[24:25], v[24:25], v[98:99] op_sel_hi:[1,0]
	v_pk_mul_f32 v[26:27], v[26:27], v[98:99] op_sel_hi:[1,0]
	v_pk_add_f32 v[40:41], v[40:41], 1.0 op_sel_hi:[1,0]
	v_pk_add_f32 v[42:43], v[42:43], 1.0 op_sel_hi:[1,0]
	v_pk_fma_f32 v[40:41], v[40:41], v[24:25], v[44:45]
	v_pk_fma_f32 v[42:43], v[42:43], v[26:27], v[46:47]
	v_cvt_pk_bf16_f32 v40, v40, v41
	v_cvt_pk_bf16_f32 v41, v42, v43
	global_store_dwordx2 v[52:53], v[40:41], off sc1
	v_pk_mul_f32 v[28:29], v[28:29], v[98:99] op_sel_hi:[1,0]
	v_pk_mul_f32 v[30:31], v[30:31], v[98:99] op_sel_hi:[1,0]
	v_pk_add_f32 v[66:67], v[66:67], 1.0 op_sel_hi:[1,0]
	v_pk_add_f32 v[68:69], v[68:69], 1.0 op_sel_hi:[1,0]
	v_pk_fma_f32 v[66:67], v[66:67], v[28:29], v[78:79]
	v_pk_fma_f32 v[68:69], v[68:69], v[30:31], v[80:81]
	v_cvt_pk_bf16_f32 v66, v66, v67
	v_cvt_pk_bf16_f32 v67, v68, v69
	global_store_dwordx2 v[52:53], v[66:67], off offset:512 sc1
	v_pk_mul_f32 v[32:33], v[32:33], v[98:99] op_sel_hi:[1,0]
	v_pk_mul_f32 v[34:35], v[34:35], v[98:99] op_sel_hi:[1,0]
	v_pk_add_f32 v[70:71], v[70:71], 1.0 op_sel_hi:[1,0]
	v_pk_add_f32 v[72:73], v[72:73], 1.0 op_sel_hi:[1,0]
	v_pk_fma_f32 v[70:71], v[70:71], v[32:33], v[82:83]
	v_pk_fma_f32 v[72:73], v[72:73], v[34:35], v[84:85]
	v_cvt_pk_bf16_f32 v70, v70, v71
	v_cvt_pk_bf16_f32 v71, v72, v73
	global_store_dwordx2 v[52:53], v[70:71], off offset:1024 sc1
	v_pk_mul_f32 v[36:37], v[36:37], v[98:99] op_sel_hi:[1,0]
	v_pk_mul_f32 v[38:39], v[38:39], v[98:99] op_sel_hi:[1,0]
	v_pk_add_f32 v[74:75], v[74:75], 1.0 op_sel_hi:[1,0]
	v_pk_add_f32 v[76:77], v[76:77], 1.0 op_sel_hi:[1,0]
	v_pk_fma_f32 v[74:75], v[74:75], v[36:37], v[86:87]
	v_pk_fma_f32 v[76:77], v[76:77], v[38:39], v[88:89]
	v_cvt_pk_bf16_f32 v74, v74, v75
	v_cvt_pk_bf16_f32 v75, v76, v77
	global_store_dwordx2 v[52:53], v[74:75], off offset:1536 sc1
	s_andn2_b64 exec, exec, s[12:13]
	s_cbranch_execz .LBB0_686

.LBB0_774:
	s_or_b64 exec, exec, s[24:25]
	v_add_u32_e32 v14, 0xffffff00, v12
	v_add_u32_e32 v12, 0xfffff8e0, v12
	s_movk_i32 s23, 0x180
	v_cmp_gt_u32_e32 vcc, s23, v12
	s_movk_i32 s23, 0xbf
	v_add_u32_e32 v15, 24, v22
	v_cndmask_b32_e32 v12, 1.0, v225, vcc
	v_cmp_lt_u32_e32 vcc, s23, v14
	s_ashr_i32 s23, s22, 31
	s_lshl_b64 s[22:23], s[22:23], 1
	v_cndmask_b32_e32 v12, v226, v12, vcc
	v_cndmask_b32_e64 v12, 1.0, v12, s[44:45]
	s_waitcnt vmcnt(0)
	v_mul_f32_e32 v0, v12, v0
	ds_write_b32 v26, v0
	v_mul_f32_e32 v0, v12, v11
	ds_write_b32 v26, v0 offset:2056
	v_mul_f32_e32 v0, v12, v16
	ds_write_b32 v26, v0 offset:4112
	v_mul_f32_e32 v0, v12, v13
	ds_write_b32 v26, v0 offset:6168
	v_mul_f32_e32 v0, v12, v18
	ds_write_b32 v26, v0 offset:8224
	v_mul_f32_e32 v0, v12, v17
	ds_write_b32 v26, v0 offset:10280
	v_mul_f32_e32 v0, v12, v27
	ds_write_b32 v26, v0 offset:12336
	v_mul_f32_e32 v0, v12, v19
	ds_write_b32 v26, v0 offset:14392
	v_mul_f32_e32 v0, v12, v29
	ds_write_b32 v26, v0 offset:16448
	v_mul_f32_e32 v0, v12, v28
	ds_write_b32 v26, v0 offset:18504
	v_mul_f32_e32 v0, v12, v31
	ds_write_b32 v26, v0 offset:20560
	v_mul_f32_e32 v0, v12, v30
	ds_write_b32 v26, v0 offset:22616
	v_mul_f32_e32 v0, v12, v33
	ds_write_b32 v26, v0 offset:24672
	v_mul_f32_e32 v0, v12, v32
	ds_write_b32 v26, v0 offset:26728
	v_mul_f32_e32 v0, v12, v35
	ds_write_b32 v26, v0 offset:28784
	v_mul_f32_e32 v0, v12, v34
	ds_write_b32 v26, v0 offset:30840
	v_mul_f32_e32 v0, v12, v37
	ds_write_b32 v26, v0 offset:32896
	v_mul_f32_e32 v0, v12, v36
	ds_write_b32 v26, v0 offset:34952
	v_mul_f32_e32 v0, v12, v39
	ds_write_b32 v26, v0 offset:37008
	v_mul_f32_e32 v0, v12, v38
	ds_write_b32 v26, v0 offset:39064
	v_mul_f32_e32 v0, v12, v41
	ds_write_b32 v26, v0 offset:41120
	v_mul_f32_e32 v0, v12, v40
	ds_write_b32 v26, v0 offset:43176
	v_mul_f32_e32 v0, v12, v43
	ds_write_b32 v26, v0 offset:45232
	v_mul_f32_e32 v0, v12, v42
	ds_write_b32 v26, v0 offset:47288
	v_mul_f32_e32 v0, v12, v45
	ds_write_b32 v26, v0 offset:49344
	v_mul_f32_e32 v0, v12, v44
	ds_write_b32 v26, v0 offset:51400
	v_mul_f32_e32 v0, v12, v47
	ds_write_b32 v26, v0 offset:53456
	v_mul_f32_e32 v0, v12, v46
	ds_write_b32 v26, v0 offset:55512
	v_mul_f32_e32 v0, v12, v49
	ds_write_b32 v26, v0 offset:57568
	v_mul_f32_e32 v0, v12, v48
	ds_write_b32 v26, v0 offset:59624
	v_mul_f32_e32 v0, v12, v51
	ds_write_b32 v26, v0 offset:61680
	v_mul_f32_e32 v0, v12, v50
	ds_write_b32 v26, v0 offset:63736
	v_add_u32_e32 v0, 4, v22
	s_waitcnt lgkmcnt(0)
	s_barrier
	ds_read2st64_b32 v[18:19], v22 offset1:1
	ds_read2st64_b32 v[28:29], v0 offset0:4 offset1:5
	s_add_u32 s18, s18, s22
	s_addc_u32 s19, s19, s23
	v_mov_b32_e32 v11, v1
	v_lshl_add_u64 v[16:17], s[18:19], 0, v[10:11]
	v_add_u32_e32 v11, 8, v22
	v_add_u32_e32 v13, 12, v22
	ds_read2st64_b32 v[30:31], v11 offset0:8 offset1:9
	ds_read2st64_b32 v[32:33], v13 offset0:12 offset1:13
	ds_read2st64_b32 v[34:35], v22 offset0:2 offset1:3
	ds_read2st64_b32 v[36:37], v0 offset0:6 offset1:7
	ds_read2st64_b32 v[38:39], v11 offset0:10 offset1:11
	ds_read2st64_b32 v[40:41], v13 offset0:14 offset1:15
	v_add_u32_e32 v0, 16, v22
	v_add_u32_e32 v11, 20, v22
	s_waitcnt lgkmcnt(6)
	v_cvt_pk_bf16_f32 v12, v18, v28
	ds_read2st64_b32 v[42:43], v0 offset0:16 offset1:17
	ds_read2st64_b32 v[44:45], v11 offset0:20 offset1:21
	ds_read2st64_b32 v[46:47], v15 offset0:24 offset1:25
	v_add_u32_e32 v18, 28, v22
	ds_read2st64_b32 v[48:49], v18 offset0:28 offset1:29
	ds_read2st64_b32 v[50:51], v0 offset0:18 offset1:19
	ds_read2st64_b32 v[52:53], v11 offset0:22 offset1:23
	v_add_u32_e32 v0, s26, v21
	v_ashrrev_i32_e32 v11, 31, v0
	ds_read2st64_b32 v[54:55], v15 offset0:26 offset1:27
	ds_read2st64_b32 v[56:57], v18 offset0:30 offset1:31
	v_mul_lo_u32 v11, s14, v11
	v_mul_lo_u32 v18, s15, v0
	v_mad_u64_u32 v[58:59], s[18:19], s14, v0, 0
	v_add3_u32 v59, v59, v11, v18
	v_add_u32_e32 v11, 64, v0
	s_waitcnt lgkmcnt(12)
	v_cvt_pk_bf16_f32 v13, v30, v32
	s_waitcnt lgkmcnt(6)
	v_cvt_pk_bf16_f32 v14, v42, v44
	s_waitcnt lgkmcnt(4)
	v_cvt_pk_bf16_f32 v15, v46, v48
	v_lshl_add_u64 v[58:59], v[58:59], 1, v[16:17]
	v_ashrrev_i32_e32 v18, 31, v11
	global_store_dwordx4 v[58:59], v[12:15], off sc1
	v_mul_lo_u32 v27, s14, v18
	v_mul_lo_u32 v28, s15, v11
	v_cvt_pk_bf16_f32 v12, v19, v29
	v_mad_u64_u32 v[18:19], s[18:19], s14, v11, 0
	v_add3_u32 v19, v19, v27, v28
	v_cvt_pk_bf16_f32 v13, v31, v33
	v_cvt_pk_bf16_f32 v14, v43, v45
	v_cvt_pk_bf16_f32 v15, v47, v49
	v_lshl_add_u64 v[18:19], v[18:19], 1, v[16:17]
	v_add_u32_e32 v11, 0x80, v0
	global_store_dwordx4 v[18:19], v[12:15], off sc1
	v_ashrrev_i32_e32 v18, 31, v11
	v_mul_lo_u32 v27, s14, v18
	v_mul_lo_u32 v28, s15, v11
	v_mad_u64_u32 v[18:19], s[18:19], s14, v11, 0
	v_add3_u32 v19, v19, v27, v28
	v_add_u32_e32 v0, 0xc0, v0
	v_cvt_pk_bf16_f32 v12, v34, v36
	v_cvt_pk_bf16_f32 v13, v38, v40
	s_waitcnt lgkmcnt(2)
	v_cvt_pk_bf16_f32 v14, v50, v52
	s_waitcnt lgkmcnt(0)
	v_cvt_pk_bf16_f32 v15, v54, v56
	v_lshl_add_u64 v[18:19], v[18:19], 1, v[16:17]
	v_ashrrev_i32_e32 v11, 31, v0
	global_store_dwordx4 v[18:19], v[12:15], off sc1
	v_mul_lo_u32 v11, s14, v11
	v_mul_lo_u32 v27, s15, v0
	v_mad_u64_u32 v[18:19], s[14:15], s14, v0, 0
	v_add3_u32 v19, v19, v11, v27
	v_cvt_pk_bf16_f32 v12, v35, v37
	v_cvt_pk_bf16_f32 v13, v39, v41
	v_cvt_pk_bf16_f32 v14, v51, v53
	v_cvt_pk_bf16_f32 v15, v55, v57
	v_lshl_add_u64 v[16:17], v[18:19], 1, v[16:17]
	global_store_dwordx4 v[16:17], v[12:15], off sc1
	s_branch .LBB0_692
